# GU/in-proj K-loop: wave-uniform half-unit flag test shortened from a v_cndmask/v_cmp ballot to one s_andn2_b64
# speedup vs baseline: 1.0054x; 1.0054x over previous
; #define PG8_STAGE(bufoff, gbase, voff) do { _Pragma("unroll") for (int _i = 0; _i < 2; ++_i) \
;         __builtin_amdgcn_global_load_lds((const unsigned*)((const char*)(gbase) + (voff)[_i]), (PG8_LAS unsigned*)(lds + (bufoff) + ldsw + _i * 8192), 16, 0, 0); } while (0)
; #define PG8_LDA(dst, b, h) do { _Pragma("unroll") for (int m = 0; m < 4; ++m) _Pragma("unroll") for (int k = 0; k < 2; ++k) dst[m][k] = *(const PG8_LAS bf16x8*)(lds + PG8_SA(b, h) + aoff + m * 2048 + k * 1024); } while (0)
; #define PG8_LDB(dst, b, h) do { _Pragma("unroll") for (int n = 0; n < 2; ++n) _Pragma("unroll") for (int k = 0; k < 2; ++k) dst[n][k] = *(const PG8_LAS bf16x8*)(lds + PG8_SB(b, h) + boff + n * 2048 + k * 1024); } while (0)
; #define PG8_MMA(ai, bj, At, Bt) do { __builtin_amdgcn_s_setprio(1); _Pragma("unroll") for (int m = 0; m < 4; ++m) _Pragma("unroll") for (int n = 0; n < 2; ++n) _Pragma("unroll") for (int k = 0; k < 2; ++k) \
;         acc[ai][bj][m][n] = __builtin_amdgcn_mfma_f32_16x16x32_bf16(Bt[n][k], At[m][k], acc[ai][bj][m][n], 0, 0, 0); __builtin_amdgcn_s_setprio(0); } while (0)
; #define PG8_WAIT_V(n) asm volatile("s_waitcnt vmcnt(" #n ")" ::: "memory")
; #define PG8_WAIT_L(n) asm volatile("s_waitcnt lgkmcnt(" #n ")" ::: "memory")
; #define PG8_BAR __builtin_amdgcn_s_barrier()
; #define PG8_SCHED __builtin_amdgcn_sched_barrier(0)
; template <class Epi, class Sched, bool ALIGN_EPI = false, bool SP2 = false>
; __device__ __forceinline__ void gemm_phase(PG8_LAS unsigned char* lds, const Gemm g, const Sched& S, const Epi& E) {
;     ...
;             PG8_LDB(B0, 0, 0); PG8_LDB(B1, 0, 1); PG8_SCHED; PG8_LDA(At, 0, 0); PG8_STAGE(PG8_SA(1, 1), a1 + hstep, voffA);
;             PG8_WAIT_V(8); PG8_WAIT_L(0); PG8_BAR; PG8_MMA(0, 0, At, B0); PG8_MMA(0, 1, At, B1); PG8_BAR; PG8_SCHED;
;             if (full) PG8_LDA(At, 0, 1); PG8_STAGE(PG8_SB(0, 0), b2, voffB); PG8_STAGE(PG8_SB(0, 1), b2 + hstep, voffB); PG8_STAGE(PG8_SA(0, 0), a2, voffA);
.LBB0_292:
	v_add_u32_e32 v0, 0x10000, v223
	ds_read_b128 v[148:151], v0
	ds_read_b128 v[152:155], v0 offset:1024
	ds_read_b128 v[156:159], v0 offset:2048
	ds_read_b128 v[160:163], v0 offset:3072
	v_add_u32_e32 v0, 0x14000, v223
	ds_read_b128 v[132:135], v0
	ds_read_b128 v[136:139], v0 offset:1024
	ds_read_b128 v[140:143], v0 offset:2048
	ds_read_b128 v[144:147], v0 offset:3072
	v_lshl_add_u64 v[2:3], s[36:37], 0, v[204:205]
	s_add_i32 m0, s31, 0xc000
	ds_read_b128 v[176:179], v224
	ds_read_b128 v[192:195], v224 offset:1024
	ds_read_b128 v[172:175], v224 offset:2048
	ds_read_b128 v[188:191], v224 offset:3072
	ds_read_b128 v[168:171], v224 offset:4096
	ds_read_b128 v[184:187], v224 offset:5120
	ds_read_b128 v[164:167], v224 offset:6144
	ds_read_b128 v[180:183], v224 offset:7168
	global_load_lds_dwordx4 v[2:3], off
	v_lshl_add_u64 v[2:3], s[36:37], 0, v[206:207]
	s_add_i32 m0, s31, 0xe000
	s_nop 0
	global_load_lds_dwordx4 v[2:3], off
	s_waitcnt vmcnt(8)
	s_waitcnt lgkmcnt(0)
	s_setprio 1
	s_barrier
	v_mfma_f32_16x16x32_bf16 v[128:131], v[148:151], v[176:179], v[128:131]
	v_mfma_f32_16x16x32_bf16 v[124:127], v[156:159], v[176:179], v[124:127]
	v_mfma_f32_16x16x32_bf16 v[112:115], v[148:151], v[172:175], v[112:115]
	v_mfma_f32_16x16x32_bf16 v[108:111], v[156:159], v[172:175], v[108:111]
	v_mfma_f32_16x16x32_bf16 v[96:99], v[148:151], v[168:171], v[96:99]
	v_mfma_f32_16x16x32_bf16 v[92:95], v[156:159], v[168:171], v[92:95]
	v_mfma_f32_16x16x32_bf16 v[80:83], v[148:151], v[164:167], v[80:83]
	v_mfma_f32_16x16x32_bf16 v[76:79], v[156:159], v[164:167], v[76:79]
	v_mfma_f32_16x16x32_bf16 v[128:131], v[152:155], v[192:195], v[128:131]
	v_mfma_f32_16x16x32_bf16 v[124:127], v[160:163], v[192:195], v[124:127]
	v_mfma_f32_16x16x32_bf16 v[112:115], v[152:155], v[188:191], v[112:115]
	v_mfma_f32_16x16x32_bf16 v[108:111], v[160:163], v[188:191], v[108:111]
	v_mfma_f32_16x16x32_bf16 v[96:99], v[152:155], v[184:187], v[96:99]
	v_mfma_f32_16x16x32_bf16 v[92:95], v[160:163], v[184:187], v[92:95]
	v_mfma_f32_16x16x32_bf16 v[80:83], v[152:155], v[180:183], v[80:83]
	v_mfma_f32_16x16x32_bf16 v[76:79], v[160:163], v[180:183], v[76:79]
	v_mfma_f32_16x16x32_bf16 v[120:123], v[132:135], v[176:179], v[120:123]
	v_mfma_f32_16x16x32_bf16 v[116:119], v[140:143], v[176:179], v[116:119]
	v_mfma_f32_16x16x32_bf16 v[104:107], v[132:135], v[172:175], v[104:107]
	v_mfma_f32_16x16x32_bf16 v[100:103], v[140:143], v[172:175], v[100:103]
	v_mfma_f32_16x16x32_bf16 v[88:91], v[132:135], v[168:171], v[88:91]
	v_mfma_f32_16x16x32_bf16 v[84:87], v[140:143], v[168:171], v[84:87]
	v_mfma_f32_16x16x32_bf16 v[72:75], v[132:135], v[164:167], v[72:75]
	v_mfma_f32_16x16x32_bf16 v[68:71], v[140:143], v[164:167], v[68:71]
	v_mfma_f32_16x16x32_bf16 v[120:123], v[136:139], v[192:195], v[120:123]
	v_mfma_f32_16x16x32_bf16 v[116:119], v[144:147], v[192:195], v[116:119]
	v_mfma_f32_16x16x32_bf16 v[104:107], v[136:139], v[188:191], v[104:107]
	v_mfma_f32_16x16x32_bf16 v[100:103], v[144:147], v[188:191], v[100:103]
	v_mfma_f32_16x16x32_bf16 v[88:91], v[136:139], v[184:187], v[88:91]
	v_mfma_f32_16x16x32_bf16 v[84:87], v[144:147], v[184:187], v[84:87]
	v_mfma_f32_16x16x32_bf16 v[72:75], v[136:139], v[180:183], v[72:75]
	v_mfma_f32_16x16x32_bf16 v[68:71], v[144:147], v[180:183], v[68:71]
	s_barrier
	s_setprio 0
	s_andn2_b64 s[4:5], exec, s[34:35]
	s_andn2_b64 vcc, exec, s[34:35]
	s_cbranch_vccnz .LBB0_294
	ds_read_b128 v[176:179], v224 offset:16384
	ds_read_b128 v[192:195], v224 offset:17408
	ds_read_b128 v[172:175], v224 offset:18432
	ds_read_b128 v[188:191], v224 offset:19456
	ds_read_b128 v[168:171], v224 offset:20480
	ds_read_b128 v[184:187], v224 offset:21504
	ds_read_b128 v[164:167], v224 offset:22528
	ds_read_b128 v[180:183], v224 offset:23552

; #define PG8_STAGE(bufoff, gbase, voff) do { _Pragma("unroll") for (int _i = 0; _i < 2; ++_i) \
;         __builtin_amdgcn_global_load_lds((const unsigned*)((const char*)(gbase) + (voff)[_i]), (PG8_LAS unsigned*)(lds + (bufoff) + ldsw + _i * 8192), 16, 0, 0); } while (0)
; #define PG8_LDA(dst, b, h) do { _Pragma("unroll") for (int m = 0; m < 4; ++m) _Pragma("unroll") for (int k = 0; k < 2; ++k) dst[m][k] = *(const PG8_LAS bf16x8*)(lds + PG8_SA(b, h) + aoff + m * 2048 + k * 1024); } while (0)
; #define PG8_LDB(dst, b, h) do { _Pragma("unroll") for (int n = 0; n < 2; ++n) _Pragma("unroll") for (int k = 0; k < 2; ++k) dst[n][k] = *(const PG8_LAS bf16x8*)(lds + PG8_SB(b, h) + boff + n * 2048 + k * 1024); } while (0)
; #define PG8_MMA(ai, bj, At, Bt) do { __builtin_amdgcn_s_setprio(1); _Pragma("unroll") for (int m = 0; m < 4; ++m) _Pragma("unroll") for (int n = 0; n < 2; ++n) _Pragma("unroll") for (int k = 0; k < 2; ++k) \
;         acc[ai][bj][m][n] = __builtin_amdgcn_mfma_f32_16x16x32_bf16(Bt[n][k], At[m][k], acc[ai][bj][m][n], 0, 0, 0); __builtin_amdgcn_s_setprio(0); } while (0)
; #define PG8_WAIT_V(n) asm volatile("s_waitcnt vmcnt(" #n ")" ::: "memory")
; #define PG8_WAIT_L(n) asm volatile("s_waitcnt lgkmcnt(" #n ")" ::: "memory")
; #define PG8_BAR __builtin_amdgcn_s_barrier()
; #define PG8_SCHED __builtin_amdgcn_sched_barrier(0)
; template <class Epi, class Sched, bool ALIGN_EPI = false, bool SP2 = false>
; __device__ __forceinline__ void gemm_phase(PG8_LAS unsigned char* lds, const Gemm g, const Sched& S, const Epi& E) {
;     ...
;             PG8_LDB(B0, 0, 0); PG8_LDB(B1, 0, 1); PG8_SCHED; PG8_LDA(At, 0, 0); PG8_STAGE(PG8_SA(1, 1), a1 + hstep, voffA);
;             PG8_WAIT_V(8); PG8_WAIT_L(0); PG8_BAR; PG8_MMA(0, 0, At, B0); PG8_MMA(0, 1, At, B1); PG8_BAR; PG8_SCHED;
;             if (full) PG8_LDA(At, 0, 1); PG8_STAGE(PG8_SB(0, 0), b2, voffB); PG8_STAGE(PG8_SB(0, 1), b2 + hstep, voffB); PG8_STAGE(PG8_SA(0, 0), a2, voffA);
.LBB0_521:
	v_add_u32_e32 v0, 0x10000, v225
	ds_read_b128 v[148:151], v0
	ds_read_b128 v[152:155], v0 offset:1024
	ds_read_b128 v[156:159], v0 offset:2048
	ds_read_b128 v[160:163], v0 offset:3072
	v_add_u32_e32 v0, 0x14000, v225
	ds_read_b128 v[132:135], v0
	ds_read_b128 v[136:139], v0 offset:1024
	ds_read_b128 v[140:143], v0 offset:2048
	ds_read_b128 v[144:147], v0 offset:3072
	v_lshl_add_u64 v[2:3], s[34:35], 0, v[204:205]
	s_add_i32 m0, s27, 0xc000
	ds_read_b128 v[176:179], v241
	ds_read_b128 v[192:195], v241 offset:1024
	ds_read_b128 v[172:175], v241 offset:2048
	ds_read_b128 v[188:191], v241 offset:3072
	ds_read_b128 v[168:171], v241 offset:4096
	ds_read_b128 v[184:187], v241 offset:5120
	ds_read_b128 v[164:167], v241 offset:6144
	ds_read_b128 v[180:183], v241 offset:7168
	global_load_lds_dwordx4 v[2:3], off
	v_lshl_add_u64 v[2:3], s[34:35], 0, v[206:207]
	s_add_i32 m0, s27, 0xe000
	s_nop 0
	global_load_lds_dwordx4 v[2:3], off
	s_waitcnt vmcnt(8)
	s_waitcnt lgkmcnt(0)
	s_setprio 1
	s_barrier
	v_mfma_f32_16x16x32_bf16 v[128:131], v[148:151], v[176:179], v[128:131]
	v_mfma_f32_16x16x32_bf16 v[124:127], v[156:159], v[176:179], v[124:127]
	v_mfma_f32_16x16x32_bf16 v[112:115], v[148:151], v[172:175], v[112:115]
	v_mfma_f32_16x16x32_bf16 v[108:111], v[156:159], v[172:175], v[108:111]
	v_mfma_f32_16x16x32_bf16 v[96:99], v[148:151], v[168:171], v[96:99]
	v_mfma_f32_16x16x32_bf16 v[92:95], v[156:159], v[168:171], v[92:95]
	v_mfma_f32_16x16x32_bf16 v[80:83], v[148:151], v[164:167], v[80:83]
	v_mfma_f32_16x16x32_bf16 v[76:79], v[156:159], v[164:167], v[76:79]
	v_mfma_f32_16x16x32_bf16 v[128:131], v[152:155], v[192:195], v[128:131]
	v_mfma_f32_16x16x32_bf16 v[124:127], v[160:163], v[192:195], v[124:127]
	v_mfma_f32_16x16x32_bf16 v[112:115], v[152:155], v[188:191], v[112:115]
	v_mfma_f32_16x16x32_bf16 v[108:111], v[160:163], v[188:191], v[108:111]
	v_mfma_f32_16x16x32_bf16 v[96:99], v[152:155], v[184:187], v[96:99]
	v_mfma_f32_16x16x32_bf16 v[92:95], v[160:163], v[184:187], v[92:95]
	v_mfma_f32_16x16x32_bf16 v[80:83], v[152:155], v[180:183], v[80:83]
	v_mfma_f32_16x16x32_bf16 v[76:79], v[160:163], v[180:183], v[76:79]
	v_mfma_f32_16x16x32_bf16 v[120:123], v[132:135], v[176:179], v[120:123]
	v_mfma_f32_16x16x32_bf16 v[116:119], v[140:143], v[176:179], v[116:119]
	v_mfma_f32_16x16x32_bf16 v[104:107], v[132:135], v[172:175], v[104:107]
	v_mfma_f32_16x16x32_bf16 v[100:103], v[140:143], v[172:175], v[100:103]
	v_mfma_f32_16x16x32_bf16 v[88:91], v[132:135], v[168:171], v[88:91]
	v_mfma_f32_16x16x32_bf16 v[84:87], v[140:143], v[168:171], v[84:87]
	v_mfma_f32_16x16x32_bf16 v[72:75], v[132:135], v[164:167], v[72:75]
	v_mfma_f32_16x16x32_bf16 v[68:71], v[140:143], v[164:167], v[68:71]
	v_mfma_f32_16x16x32_bf16 v[120:123], v[136:139], v[192:195], v[120:123]
	v_mfma_f32_16x16x32_bf16 v[116:119], v[144:147], v[192:195], v[116:119]
	v_mfma_f32_16x16x32_bf16 v[104:107], v[136:139], v[188:191], v[104:107]
	v_mfma_f32_16x16x32_bf16 v[100:103], v[144:147], v[188:191], v[100:103]
	v_mfma_f32_16x16x32_bf16 v[88:91], v[136:139], v[184:187], v[88:91]
	v_mfma_f32_16x16x32_bf16 v[84:87], v[144:147], v[184:187], v[84:87]
	v_mfma_f32_16x16x32_bf16 v[72:75], v[136:139], v[180:183], v[72:75]
	v_mfma_f32_16x16x32_bf16 v[68:71], v[144:147], v[180:183], v[68:71]
	s_barrier
	s_setprio 0
	s_andn2_b64 s[4:5], exec, s[30:31]
	s_andn2_b64 vcc, exec, s[30:31]
	s_cbranch_vccnz .LBB0_523
	ds_read_b128 v[176:179], v241 offset:16384
	ds_read_b128 v[192:195], v241 offset:17408
	ds_read_b128 v[172:175], v241 offset:18432
	ds_read_b128 v[188:191], v241 offset:19456
	ds_read_b128 v[168:171], v241 offset:20480
	ds_read_b128 v[184:187], v241 offset:21504
	ds_read_b128 v[164:167], v241 offset:22528
	ds_read_b128 v[180:183], v241 offset:23552
